# v105 + bfe/and mask application in the attention loops (validated as v108)
# baseline (speedup 1.0000x reference)
; #define MFMA16(a, b, c) __builtin_amdgcn_mfma_f32_16x16x32_bf16((a), (b), (c), 0, 0, 0)
; DI void attn_block(const Params& p, int isP, int sq, int c, int h) {
;     ...
;     for (; s < nsteps; s += 4) {
;       const int sn = (s + 4 < nsteps) ? s + 4 : s;
;       const bfr* pa = kptr + (long)sn * 32 * 512;
;       const bf16x8 nka0 = *(const bf16x8*)pa, nka1 = *(const bf16x8*)(pa + 32);
;       const bf16x8 nkb0 = *(const bf16x8*)(pa + 4 * 512), nkb1 = *(const bf16x8*)(pa + 4 * 512 + 32);
;       bf16x8 nvf[4];
; #pragma unroll
;       for (int dt = 0; dt < 4; ++dt) nvf[dt] = *(const bf16x8*)(vptr + (long)dt * 16 * vld + sn * 32);
;       unsigned nmw[4];
; #pragma unroll
;       for (int qt = 0; qt < 4; ++qt) nmw[qt] = mrow[qt][sn];
; #pragma unroll
;       for (int qt = 0; qt < 4; ++qt) {
;         if (qt < nqt) {
;           f32x4 sa = {0.f, 0.f, 0.f, 0.f}, sb = {0.f, 0.f, 0.f, 0.f};
;           sa = MFMA16(ka0, qf[qt][0], sa); sa = MFMA16(ka1, qf[qt][1], sa);
;           sb = MFMA16(kb0, qf[qt][0], sb); sb = MFMA16(kb1, qf[qt][1], sb);
;           const unsigned mb = (mw[qt] >> (fq * 8)) & 0xFFu;
;           float pr[8];
; #pragma unroll
;           for (int i = 0; i < 4; ++i) {
;             float pa_ = __builtin_amdgcn_exp2f(sa[i] * sc2 - mref[qt]);
;             float pb_ = __builtin_amdgcn_exp2f(sb[i] * sc2 - mref[qt]);
;             pr[i] = ((mb >> i) & 1u) ? pa_ : 0.f;
;             pr[4 + i] = ((mb >> (4 + i)) & 1u) ? pb_ : 0.f;
;           }
;           lsum[qt] += ((pr[0] + pr[1]) + (pr[2] + pr[3])) + ((pr[4] + pr[5]) + (pr[6] + pr[7]));
;           union { unsigned u[4]; bf16x8 v; } pk;
;           pk.u[0] = pack2(pr[0], pr[1]); pk.u[1] = pack2(pr[2], pr[3]); pk.u[2] = pack2(pr[4], pr[5]); pk.u[3] = pack2(pr[6], pr[7]);
; #pragma unroll
;           for (int dt = 0; dt < 4; ++dt) o[qt][dt] = MFMA16(vf[dt], pk.v, o[qt][dt]);
;         }
;       }
;       ka0 = nka0; ka1 = nka1; kb0 = nkb0; kb1 = nkb1;
; #pragma unroll
;       for (int dt = 0; dt < 4; ++dt) vf[dt] = nvf[dt];
; #pragma unroll
;       for (int qt = 0; qt < 4; ++qt) mw[qt] = nmw[qt];
;     }
.LBB0_4853:
	s_ashr_i32 s1, s0, 31
	v_lshl_add_u64 v[126:127], s[0:1], 1, v[102:103]
	v_lshl_add_u64 v[136:137], v[114:115], 0, s[36:37]
	s_mov_b32 s1, 0x187a1000
	v_add_co_u32_e32 v132, vcc, s1, v136
	s_mov_b32 s1, 0x187a0000
	s_nop 0
	v_addc_co_u32_e32 v133, vcc, 0, v137, vcc
	v_add_co_u32_e32 v140, vcc, s1, v136
	global_load_dwordx4 v[122:125], v[132:133], off offset:3136
	s_nop 0
	global_load_dwordx4 v[132:135], v[132:133], off offset:3072
	v_addc_co_u32_e32 v141, vcc, 0, v137, vcc
	global_load_dwordx4 v[136:139], v[140:141], off offset:3136
	s_nop 0
	global_load_dwordx4 v[140:143], v[140:141], off offset:3072
	v_lshl_add_u64 v[144:145], v[106:107], 0, s[36:37]
	global_load_dword v156, v[144:145], off
	v_lshl_add_u64 v[144:145], v[108:109], 0, s[36:37]
	global_load_dword v157, v[144:145], off
	s_mov_b32 s1, 0x10000
	v_add_co_u32_e32 v148, vcc, s1, v126
	s_mov_b32 s1, 0x21000
	s_nop 0
	v_addc_co_u32_e32 v149, vcc, 0, v127, vcc
	v_lshl_add_u64 v[144:145], v[110:111], 0, s[36:37]
	v_add_co_u32_e32 v152, vcc, s1, v126
	global_load_dword v159, v[144:145], off
	v_lshl_add_u64 v[144:145], v[112:113], 0, s[36:37]
	v_addc_co_u32_e32 v153, vcc, 0, v127, vcc
	s_mov_b32 s1, 0x31000
	global_load_dword v202, v[144:145], off
	s_nop 0
	global_load_dwordx4 v[144:147], v[126:127], off
	v_add_co_u32_e32 v126, vcc, s1, v126
	global_load_dwordx4 v[148:151], v[148:149], off offset:2048
	s_nop 0
	v_addc_co_u32_e32 v127, vcc, 0, v127, vcc
	global_load_dwordx4 v[152:155], v[152:153], off
	s_add_i32 s8, s8, 4
	global_load_dwordx4 v[180:183], v[126:127], off offset:2048
	s_addk_i32 s0, 0x80
	v_lshl_add_u64 v[106:107], v[106:107], 0, 16
	v_lshl_add_u64 v[108:109], v[108:109], 0, 16
	v_lshl_add_u64 v[110:111], v[110:111], 0, 16
	v_lshl_add_u64 v[112:113], v[112:113], 0, 16
	v_lshl_add_u64 v[114:115], v[114:115], 0, s[22:23]
	s_cmp_lt_i32 s8, 62
	s_waitcnt vmcnt(10)
	v_mfma_f32_16x16x32_bf16 v[188:191], v[132:135], v[8:11], 0
	s_waitcnt vmcnt(7)
	v_lshrrev_b32_e32 v204, v98, v156
	v_mfma_f32_16x16x32_bf16 v[184:187], v[140:143], v[8:11], 0
	s_waitcnt vmcnt(6)
	v_lshrrev_b32_e32 v203, v97, v157
	v_bfe_i32 v212, v203, 0, 1
	v_bfe_i32 v213, v204, 0, 1
	v_mfma_f32_16x16x32_bf16 v[188:191], v[122:125], v[16:19], v[188:191]
	v_bfe_i32 v214, v203, 1, 1
	s_waitcnt vmcnt(5)
	v_lshrrev_b32_e32 v159, v98, v159
	v_mfma_f32_16x16x32_bf16 v[184:187], v[136:139], v[16:19], v[184:187]
	s_nop 2
	v_fma_f32 v127, v188, s33, -v118
	v_exp_f32_e32 v192, v127
	s_nop 2
	v_fma_f32 v127, v185, s33, -v118
	v_exp_f32_e32 v193, v127
	v_fma_f32 v127, v189, s33, -v118
	v_exp_f32_e32 v194, v127
	v_fma_f32 v127, v186, s33, -v118
	v_exp_f32_e32 v195, v127
	v_fma_f32 v127, v190, s33, -v118
	v_fma_f32 v126, v184, s33, -v118
	v_exp_f32_e32 v196, v127
	v_fma_f32 v127, v187, s33, -v118
	v_mfma_f32_16x16x32_bf16 v[184:187], v[140:143], v[28:31], 0
	v_exp_f32_e32 v197, v127
	v_fma_f32 v127, v191, s33, -v118
	v_exp_f32_e32 v198, v127
	v_mfma_f32_16x16x32_bf16 v[188:191], v[132:135], v[28:31], 0
	v_exp_f32_e32 v126, v126
	v_mfma_f32_16x16x32_bf16 v[184:187], v[136:139], v[32:35], v[184:187]
	v_mfma_f32_16x16x32_bf16 v[188:191], v[122:125], v[32:35], v[188:191]
	s_nop 6
	v_fma_f32 v127, v184, s33, -v119
	v_exp_f32_e32 v127, v127
	v_fma_f32 v185, v185, s33, -v119
	v_fma_f32 v184, v188, s33, -v119
	v_exp_f32_e32 v185, v185
	v_fma_f32 v188, v189, s33, -v119
	v_exp_f32_e32 v199, v188
	v_fma_f32 v186, v186, s33, -v119
	v_fma_f32 v188, v190, s33, -v119
	v_exp_f32_e32 v186, v186
	v_exp_f32_e32 v200, v188
	v_fma_f32 v188, v191, s33, -v119
	v_and_b32_e32 v127, v127, v212
	v_fma_f32 v187, v187, s33, -v119
	v_exp_f32_e32 v201, v188
	v_and_b32_e32 v126, v126, v213
	v_bfe_i32 v215, v204, 1, 1
	v_exp_f32_e32 v187, v187
	v_exp_f32_e32 v184, v184
	v_and_b32_e32 v157, v185, v214
	v_bfe_i32 v216, v203, 2, 1
	v_bfe_i32 v217, v204, 2, 1
	v_and_b32_e32 v156, v193, v215
	v_bfe_i32 v218, v203, 3, 1
	s_nop 0
	v_and_b32_e32 v189, v186, v216
	v_bfe_i32 v219, v204, 3, 1
	s_nop 0
	v_and_b32_e32 v188, v195, v217
	v_bfe_i32 v220, v203, 4, 1
	s_nop 0
	v_and_b32_e32 v191, v187, v218
	v_bfe_i32 v221, v204, 4, 1
	s_nop 0
	v_and_b32_e32 v190, v197, v219
	v_bfe_i32 v223, v204, 5, 1
	s_nop 0
	v_and_b32_e32 v193, v184, v220
	v_bfe_i32 v222, v203, 5, 1
	v_pk_add_f32 v[186:187], v[188:189], v[190:191]
	v_and_b32_e32 v192, v192, v221
	v_bfe_i32 v224, v203, 6, 1
	s_nop 0
	v_and_b32_e32 v195, v199, v222
	v_bfe_i32 v225, v204, 6, 1
	s_nop 0
	v_and_b32_e32 v194, v194, v223
	v_bfe_i32 v226, v203, 7, 1
	s_nop 0
	v_and_b32_e32 v197, v200, v224
	v_bfe_i32 v227, v204, 7, 1
	s_nop 0
	v_and_b32_e32 v196, v196, v225
	s_nop 1
	v_and_b32_e32 v199, v201, v226
	v_pk_add_f32 v[184:185], v[126:127], v[156:157]
	s_nop 0
	v_and_b32_e32 v198, v198, v227
	v_pk_add_f32 v[184:185], v[184:185], v[186:187]
	v_pk_add_f32 v[186:187], v[192:193], v[194:195]
	v_pk_add_f32 v[200:201], v[196:197], v[198:199]
	s_nop 0
	v_pk_add_f32 v[186:187], v[186:187], v[200:201]
	s_nop 0
	v_pk_add_f32 v[200:201], v[184:185], v[186:187]
	v_cvt_pk_bf16_f32 v184, v126, v156
	v_cvt_pk_bf16_f32 v185, v188, v190
	v_cvt_pk_bf16_f32 v186, v192, v194
	v_cvt_pk_bf16_f32 v187, v196, v198
	v_pk_add_f32 v[104:105], v[104:105], v[200:201]
	s_waitcnt vmcnt(3)
; #define MFMA16(a, b, c) __builtin_amdgcn_mfma_f32_16x16x32_bf16((a), (b), (c), 0, 0, 0)
; DI void attn_block(const Params& p, int isP, int sq, int c, int h) {
;     ...
;       for (int qt = 0; qt < 4; ++qt) {
;         if (qt < nqt) {
;           f32x4 sa = {0.f, 0.f, 0.f, 0.f}, sb = {0.f, 0.f, 0.f, 0.f};
;           sa = MFMA16(ka0, qf[qt][0], sa); sa = MFMA16(ka1, qf[qt][1], sa);
;           sb = MFMA16(kb0, qf[qt][0], sb); sb = MFMA16(kb1, qf[qt][1], sb);
;           const unsigned mb = (mw[qt] >> (fq * 8)) & 0xFFu;
;           float pr[8];
; #pragma unroll
;           for (int i = 0; i < 4; ++i) {
;             float pa_ = __builtin_amdgcn_exp2f(sa[i] * sc2 - mref[qt]);
;             float pb_ = __builtin_amdgcn_exp2f(sb[i] * sc2 - mref[qt]);
;             pr[i] = ((mb >> i) & 1u) ? pa_ : 0.f;
;             pr[4 + i] = ((mb >> (4 + i)) & 1u) ? pb_ : 0.f;
;           }
;           lsum[qt] += ((pr[0] + pr[1]) + (pr[2] + pr[3])) + ((pr[4] + pr[5]) + (pr[6] + pr[7]));
;           union { unsigned u[4]; bf16x8 v; } pk;
;           pk.u[0] = pack2(pr[0], pr[1]); pk.u[1] = pack2(pr[2], pr[3]); pk.u[2] = pack2(pr[4], pr[5]); pk.u[3] = pack2(pr[6], pr[7]);
; #pragma unroll
;           for (int dt = 0; dt < 4; ++dt) o[qt][dt] = MFMA16(vf[dt], pk.v, o[qt][dt]);
;         }
;       }
;       ka0 = nka0; ka1 = nka1; kb0 = nkb0; kb1 = nkb1;
; #pragma unroll
;       for (int dt = 0; dt < 4; ++dt) vf[dt] = nvf[dt];
; #pragma unroll
;       for (int qt = 0; qt < 4; ++qt) mw[qt] = nmw[qt];
;     }
	v_mfma_f32_16x16x32_bf16 v[64:67], v[144:147], v[184:187], v[64:67]
	s_waitcnt vmcnt(2)
	v_mfma_f32_16x16x32_bf16 v[92:95], v[148:151], v[184:187], v[92:95]
	s_waitcnt vmcnt(1)
	v_mfma_f32_16x16x32_bf16 v[88:91], v[152:155], v[184:187], v[88:91]
	s_waitcnt vmcnt(0)
	v_mfma_f32_16x16x32_bf16 v[84:87], v[180:183], v[184:187], v[84:87]
	v_cvt_pk_bf16_f32 v184, v127, v157
	v_cvt_pk_bf16_f32 v185, v189, v191
	v_cvt_pk_bf16_f32 v186, v193, v195
	v_cvt_pk_bf16_f32 v187, v197, v199
	v_mfma_f32_16x16x32_bf16 v[188:191], v[132:135], v[48:51], 0
	s_nop 0
	v_mfma_f32_16x16x32_bf16 v[80:83], v[144:147], v[184:187], v[80:83]
	v_mfma_f32_16x16x32_bf16 v[76:79], v[148:151], v[184:187], v[76:79]
	v_mfma_f32_16x16x32_bf16 v[72:75], v[152:155], v[184:187], v[72:75]
	v_mfma_f32_16x16x32_bf16 v[68:71], v[180:183], v[184:187], v[68:71]
	v_mfma_f32_16x16x32_bf16 v[184:187], v[140:143], v[48:51], 0
	v_mfma_f32_16x16x32_bf16 v[188:191], v[122:125], v[52:55], v[188:191]
	v_mfma_f32_16x16x32_bf16 v[184:187], v[136:139], v[52:55], v[184:187]
	v_mfma_f32_16x16x32_bf16 v[140:143], v[140:143], v[56:59], 0
	s_nop 5
	v_fma_f32 v127, v188, s33, -v120
	v_exp_f32_e32 v156, v127
	v_fma_f32 v127, v185, s33, -v120
	v_exp_f32_e32 v157, v127
	v_fma_f32 v127, v189, s33, -v120
	v_fma_f32 v126, v184, s33, -v120
	v_exp_f32_e32 v184, v127
	v_fma_f32 v127, v186, s33, -v120
	v_mfma_f32_16x16x32_bf16 v[136:139], v[136:139], v[60:63], v[140:143]
	v_exp_f32_e32 v185, v127
	v_fma_f32 v127, v190, s33, -v120
	v_exp_f32_e32 v186, v127
	v_mfma_f32_16x16x32_bf16 v[132:135], v[132:135], v[56:59], 0
	v_fma_f32 v127, v187, s33, -v120
	v_exp_f32_e32 v187, v127
	v_fma_f32 v127, v191, s33, -v120
	v_exp_f32_e32 v188, v127
	v_fma_f32 v127, v136, s33, -v121
	v_mfma_f32_16x16x32_bf16 v[122:125], v[122:125], v[60:63], v[132:135]
	v_exp_f32_e32 v127, v127
	v_exp_f32_e32 v126, v126
	v_lshrrev_b32_e32 v189, v97, v202
	v_fma_f32 v133, v138, s33, -v121
	v_fma_f32 v132, v137, s33, -v121
	v_exp_f32_e32 v134, v133
	v_fma_f32 v133, v139, s33, -v121
	v_exp_f32_e32 v132, v132
	v_exp_f32_e32 v136, v133
	v_bfe_i32 v212, v189, 0, 1
	v_bfe_i32 v213, v159, 0, 1
	v_bfe_i32 v214, v189, 1, 1
	v_fma_f32 v122, v122, s33, -v121
	v_and_b32_e32 v127, v127, v212
	v_bfe_i32 v215, v159, 1, 1
	v_bfe_i32 v217, v159, 2, 1
	v_and_b32_e32 v126, v126, v213
	v_exp_f32_e32 v122, v122
	v_fma_f32 v123, v123, s33, -v121
	v_and_b32_e32 v133, v132, v214
	v_bfe_i32 v216, v189, 2, 1
	v_bfe_i32 v219, v159, 3, 1
	v_and_b32_e32 v132, v157, v215
	v_exp_f32_e32 v123, v123
	v_fma_f32 v124, v124, s33, -v121
	v_and_b32_e32 v135, v134, v216
	v_bfe_i32 v218, v189, 3, 1
	v_bfe_i32 v221, v159, 4, 1
	v_and_b32_e32 v134, v185, v217
	v_exp_f32_e32 v124, v124
	v_fma_f32 v125, v125, s33, -v121
	v_and_b32_e32 v137, v136, v218
	v_bfe_i32 v220, v189, 4, 1
	v_exp_f32_e32 v125, v125
	v_and_b32_e32 v136, v187, v219
	s_nop 1
	v_and_b32_e32 v139, v122, v220
	v_bfe_i32 v222, v189, 5, 1
	v_bfe_i32 v223, v159, 5, 1
	v_and_b32_e32 v138, v156, v221
	v_bfe_i32 v224, v189, 6, 1
	s_nop 0
	v_and_b32_e32 v141, v123, v222
	v_bfe_i32 v225, v159, 6, 1
	s_nop 0
	v_and_b32_e32 v140, v184, v223
	v_bfe_i32 v226, v189, 7, 1
	s_nop 0
	v_and_b32_e32 v143, v124, v224
	v_bfe_i32 v227, v159, 7, 1
	s_nop 0
	v_and_b32_e32 v142, v186, v225
	s_nop 1
	v_and_b32_e32 v157, v125, v226
	v_pk_add_f32 v[122:123], v[126:127], v[132:133]
	v_pk_add_f32 v[124:125], v[134:135], v[136:137]
	v_and_b32_e32 v156, v188, v227
	v_pk_add_f32 v[122:123], v[122:123], v[124:125]
	v_pk_add_f32 v[124:125], v[138:139], v[140:141]
	v_pk_add_f32 v[184:185], v[142:143], v[156:157]
	s_nop 0
	v_pk_add_f32 v[124:125], v[124:125], v[184:185]
	s_nop 0
	v_pk_add_f32 v[184:185], v[122:123], v[124:125]
	v_cvt_pk_bf16_f32 v122, v126, v132
	v_cvt_pk_bf16_f32 v123, v134, v136
	v_cvt_pk_bf16_f32 v124, v138, v140
	v_cvt_pk_bf16_f32 v125, v142, v156
	v_pk_add_f32 v[100:101], v[100:101], v[184:185]
	s_nop 0
	v_mfma_f32_16x16x32_bf16 v[44:47], v[144:147], v[122:125], v[44:47]
	v_mfma_f32_16x16x32_bf16 v[40:43], v[148:151], v[122:125], v[40:43]
	v_mfma_f32_16x16x32_bf16 v[36:39], v[152:155], v[122:125], v[36:39]
	v_mfma_f32_16x16x32_bf16 v[24:27], v[180:183], v[122:125], v[24:27]
	v_cvt_pk_bf16_f32 v122, v127, v133
	v_cvt_pk_bf16_f32 v123, v135, v137
	v_cvt_pk_bf16_f32 v124, v139, v141
	v_cvt_pk_bf16_f32 v125, v143, v157
	s_nop 1
	v_mfma_f32_16x16x32_bf16 v[20:23], v[144:147], v[122:125], v[20:23]
	v_mfma_f32_16x16x32_bf16 v[12:15], v[148:151], v[122:125], v[12:15]
	v_mfma_f32_16x16x32_bf16 v[4:7], v[152:155], v[122:125], v[4:7]
	v_mfma_f32_16x16x32_bf16 v[0:3], v[180:183], v[122:125], v[0:3]
	s_cbranch_scc1 .LBB0_4853

; #define MFMA16(a, b, c) __builtin_amdgcn_mfma_f32_16x16x32_bf16((a), (b), (c), 0, 0, 0)
; DI void attn_block(const Params& p, int isP, int sq, int c, int h) {
;     ...
;     for (; s < nsteps; s += 4) {
;       const int sn = (s + 4 < nsteps) ? s + 4 : s;
;       const bfr* pa = kptr + (long)sn * 32 * 512;
;       const bf16x8 nka0 = *(const bf16x8*)pa, nka1 = *(const bf16x8*)(pa + 32);
;       const bf16x8 nkb0 = *(const bf16x8*)(pa + 4 * 512), nkb1 = *(const bf16x8*)(pa + 4 * 512 + 32);
;       bf16x8 nvf[4];
; #pragma unroll
;       for (int dt = 0; dt < 4; ++dt) nvf[dt] = *(const bf16x8*)(vptr + (long)dt * 16 * vld + sn * 32);
;       unsigned nmw[4];
; #pragma unroll
;       for (int qt = 0; qt < 4; ++qt) nmw[qt] = mrow[qt][sn];
; #pragma unroll
;       for (int qt = 0; qt < 4; ++qt) {
;         if (qt < nqt) {
;           f32x4 sa = {0.f, 0.f, 0.f, 0.f}, sb = {0.f, 0.f, 0.f, 0.f};
;           sa = MFMA16(ka0, qf[qt][0], sa); sa = MFMA16(ka1, qf[qt][1], sa);
;           sb = MFMA16(kb0, qf[qt][0], sb); sb = MFMA16(kb1, qf[qt][1], sb);
;           const unsigned mb = (mw[qt] >> (fq * 8)) & 0xFFu;
;           float pr[8];
; #pragma unroll
;           for (int i = 0; i < 4; ++i) {
;             float pa_ = __builtin_amdgcn_exp2f(sa[i] * sc2 - mref[qt]);
;             float pb_ = __builtin_amdgcn_exp2f(sb[i] * sc2 - mref[qt]);
;             pr[i] = ((mb >> i) & 1u) ? pa_ : 0.f;
;             pr[4 + i] = ((mb >> (4 + i)) & 1u) ? pb_ : 0.f;
;           }
;           lsum[qt] += ((pr[0] + pr[1]) + (pr[2] + pr[3])) + ((pr[4] + pr[5]) + (pr[6] + pr[7]));
;           union { unsigned u[4]; bf16x8 v; } pk;
;           pk.u[0] = pack2(pr[0], pr[1]); pk.u[1] = pack2(pr[2], pr[3]); pk.u[2] = pack2(pr[4], pr[5]); pk.u[3] = pack2(pr[6], pr[7]);
; #pragma unroll
;           for (int dt = 0; dt < 4; ++dt) o[qt][dt] = MFMA16(vf[dt], pk.v, o[qt][dt]);
;         }
;       }
;       ka0 = nka0; ka1 = nka1; kb0 = nkb0; kb1 = nkb1;
; #pragma unroll
;       for (int dt = 0; dt < 4; ++dt) vf[dt] = nvf[dt];
; #pragma unroll
;       for (int qt = 0; qt < 4; ++qt) mw[qt] = nmw[qt];
;     }
.LBB0_4861:
	v_lshl_add_u64 v[96:97], v[156:157], 0, s[36:37]
	v_add_co_u32_e32 v98, vcc, s8, v96
	s_ashr_i32 s1, s0, 31
	s_nop 0
	v_addc_co_u32_e32 v99, vcc, 0, v97, vcc
	v_add_co_u32_e32 v96, vcc, s9, v96
	global_load_dwordx4 v[112:115], v[98:99], off offset:3136
	global_load_dwordx4 v[116:119], v[98:99], off offset:3072
	v_addc_co_u32_e32 v97, vcc, 0, v97, vcc
	global_load_dwordx4 v[120:123], v[96:97], off offset:3136
	global_load_dwordx4 v[124:127], v[96:97], off offset:3072
	ds_read_b32 v128, v208
	ds_read_b32 v159, v208 offset:8448
	v_lshl_add_u64 v[108:109], s[0:1], 1, v[144:145]
	s_mov_b32 s1, 0x20000
	v_add_co_u32_e32 v100, vcc, s1, v108
	s_mov_b32 s1, 0x40000
	s_nop 0
	v_addc_co_u32_e32 v101, vcc, 0, v109, vcc
	v_add_co_u32_e32 v104, vcc, s1, v108
	ds_read_b32 v185, v208 offset:16896
	v_addc_co_u32_e32 v105, vcc, 0, v109, vcc
	s_mov_b32 s1, 0x60000
	ds_read_b32 v204, v208 offset:25344
	s_add_i32 s7, s7, 4
	global_load_dwordx4 v[96:99], v[108:109], off
	v_add_co_u32_e32 v108, vcc, s1, v108
	global_load_dwordx4 v[100:103], v[100:101], off offset:1024
	s_nop 0
	v_addc_co_u32_e32 v109, vcc, 0, v109, vcc
	global_load_dwordx4 v[104:107], v[104:105], off offset:2048
	s_addk_i32 s0, 0x80
	global_load_dwordx4 v[108:111], v[108:109], off offset:3072
	v_add_u32_e32 v208, 16, v208
	v_lshl_add_u64 v[156:157], v[156:157], 0, s[22:23]
	s_cmp_le_i32 s7, s21
	s_waitcnt vmcnt(6)
	v_mfma_f32_16x16x32_bf16 v[186:189], v[116:119], v[16:19], 0
	s_waitcnt vmcnt(4) lgkmcnt(3)
	v_lshrrev_b32_e32 v128, v140, v128
	v_mfma_f32_16x16x32_bf16 v[132:135], v[124:127], v[16:19], 0
	s_waitcnt lgkmcnt(2)
	v_lshrrev_b32_e32 v159, v137, v159
	s_waitcnt lgkmcnt(1)
	v_lshrrev_b32_e32 v185, v140, v185
	v_mfma_f32_16x16x32_bf16 v[132:135], v[120:123], v[24:27], v[132:135]
	v_mfma_f32_16x16x32_bf16 v[186:189], v[112:115], v[24:27], v[186:189]
	s_nop 6
	v_fma_f32 v132, v132, s33, -v181
	v_exp_f32_e32 v190, v132
	v_fma_f32 v132, v186, s33, -v181
	v_exp_f32_e32 v194, v132
	v_fma_f32 v132, v133, s33, -v181
	v_exp_f32_e32 v191, v132
	v_fma_f32 v132, v187, s33, -v181
	v_exp_f32_e32 v196, v132
	v_fma_f32 v132, v134, s33, -v181
	v_exp_f32_e32 v192, v132
	v_fma_f32 v132, v188, s33, -v181
	v_exp_f32_e32 v198, v132
	v_fma_f32 v132, v135, s33, -v181
	v_exp_f32_e32 v195, v132
	v_fma_f32 v132, v189, s33, -v181
	v_mfma_f32_16x16x32_bf16 v[186:189], v[116:119], v[36:39], 0
	v_exp_f32_e32 v200, v132
	v_mfma_f32_16x16x32_bf16 v[132:135], v[124:127], v[36:39], 0
	v_mfma_f32_16x16x32_bf16 v[186:189], v[112:115], v[44:47], v[186:189]
	v_mfma_f32_16x16x32_bf16 v[132:135], v[120:123], v[44:47], v[132:135]
	s_nop 6
	v_fma_f32 v186, v186, s33, -v182
	v_fma_f32 v132, v132, s33, -v182
	v_exp_f32_e32 v197, v186
	v_fma_f32 v186, v187, s33, -v182
	v_exp_f32_e32 v132, v132
	v_exp_f32_e32 v199, v186
	v_fma_f32 v186, v188, s33, -v182
	v_fma_f32 v133, v133, s33, -v182
	v_exp_f32_e32 v201, v186
	v_fma_f32 v186, v189, s33, -v182
	v_exp_f32_e32 v133, v133
	v_exp_f32_e32 v202, v186
	v_bfe_i32 v212, v159, 0, 1
	v_fma_f32 v134, v134, s33, -v182
	v_bfe_i32 v213, v128, 0, 1
	v_exp_f32_e32 v134, v134
	v_fma_f32 v135, v135, s33, -v182
	v_and_b32_e32 v187, v132, v212
	v_bfe_i32 v214, v159, 1, 1
	v_bfe_i32 v215, v128, 1, 1
	v_and_b32_e32 v186, v190, v213
	v_exp_f32_e32 v135, v135
	v_bfe_i32 v216, v159, 2, 1
	v_and_b32_e32 v189, v133, v214
	v_bfe_i32 v217, v128, 2, 1
	s_nop 0
	v_and_b32_e32 v188, v191, v215
	v_bfe_i32 v218, v159, 3, 1
	s_nop 0
	v_and_b32_e32 v191, v134, v216
	v_bfe_i32 v219, v128, 3, 1
	s_nop 0
	v_and_b32_e32 v190, v192, v217
	v_bfe_i32 v220, v159, 4, 1
	s_nop 0
	v_and_b32_e32 v193, v135, v218
	v_bfe_i32 v221, v128, 4, 1
	s_nop 0
	v_and_b32_e32 v192, v195, v219
	v_bfe_i32 v222, v159, 5, 1
	v_pk_add_f32 v[134:135], v[190:191], v[192:193]
	v_and_b32_e32 v195, v197, v220
	v_bfe_i32 v223, v128, 5, 1
	s_nop 0
	v_and_b32_e32 v194, v194, v221
	v_bfe_i32 v224, v159, 6, 1
	s_nop 0
	v_and_b32_e32 v197, v199, v222
	v_bfe_i32 v225, v128, 6, 1
	v_bfe_i32 v227, v128, 7, 1
	v_and_b32_e32 v196, v196, v223
	v_bfe_i32 v226, v159, 7, 1
	s_nop 0
	v_and_b32_e32 v199, v201, v224
	s_nop 1
	v_and_b32_e32 v198, v198, v225
	v_pk_add_f32 v[132:133], v[186:187], v[188:189]
	s_nop 0
	v_and_b32_e32 v201, v202, v226
	v_pk_add_f32 v[132:133], v[132:133], v[134:135]
	v_pk_add_f32 v[134:135], v[194:195], v[196:197]
	v_and_b32_e32 v200, v200, v227
	v_pk_add_f32 v[202:203], v[198:199], v[200:201]
	s_nop 0
	v_pk_add_f32 v[134:135], v[134:135], v[202:203]
	s_nop 0
	v_pk_add_f32 v[202:203], v[132:133], v[134:135]
	v_cvt_pk_bf16_f32 v132, v186, v188
	v_cvt_pk_bf16_f32 v133, v190, v192
	v_cvt_pk_bf16_f32 v134, v194, v196
	v_cvt_pk_bf16_f32 v135, v198, v200
	v_pk_add_f32 v[146:147], v[146:147], v[202:203]
	s_waitcnt vmcnt(3)
; #define MFMA16(a, b, c) __builtin_amdgcn_mfma_f32_16x16x32_bf16((a), (b), (c), 0, 0, 0)
; DI void attn_block(const Params& p, int isP, int sq, int c, int h) {
;     ...
;       for (int qt = 0; qt < 4; ++qt) {
;         if (qt < nqt) {
;           f32x4 sa = {0.f, 0.f, 0.f, 0.f}, sb = {0.f, 0.f, 0.f, 0.f};
;           sa = MFMA16(ka0, qf[qt][0], sa); sa = MFMA16(ka1, qf[qt][1], sa);
;           sb = MFMA16(kb0, qf[qt][0], sb); sb = MFMA16(kb1, qf[qt][1], sb);
;           const unsigned mb = (mw[qt] >> (fq * 8)) & 0xFFu;
;           float pr[8];
; #pragma unroll
;           for (int i = 0; i < 4; ++i) {
;             float pa_ = __builtin_amdgcn_exp2f(sa[i] * sc2 - mref[qt]);
;             float pb_ = __builtin_amdgcn_exp2f(sb[i] * sc2 - mref[qt]);
;             pr[i] = ((mb >> i) & 1u) ? pa_ : 0.f;
;             pr[4 + i] = ((mb >> (4 + i)) & 1u) ? pb_ : 0.f;
;           }
;           lsum[qt] += ((pr[0] + pr[1]) + (pr[2] + pr[3])) + ((pr[4] + pr[5]) + (pr[6] + pr[7]));
;           union { unsigned u[4]; bf16x8 v; } pk;
;           pk.u[0] = pack2(pr[0], pr[1]); pk.u[1] = pack2(pr[2], pr[3]); pk.u[2] = pack2(pr[4], pr[5]); pk.u[3] = pack2(pr[6], pr[7]);
; #pragma unroll
;           for (int dt = 0; dt < 4; ++dt) o[qt][dt] = MFMA16(vf[dt], pk.v, o[qt][dt]);
;         }
;       }
;       ka0 = nka0; ka1 = nka1; kb0 = nkb0; kb1 = nkb1;
; #pragma unroll
;       for (int dt = 0; dt < 4; ++dt) vf[dt] = nvf[dt];
; #pragma unroll
;       for (int qt = 0; qt < 4; ++qt) mw[qt] = nmw[qt];
;     }
	v_mfma_f32_16x16x32_bf16 v[64:67], v[96:99], v[132:135], v[64:67]
	s_waitcnt vmcnt(2)
	v_mfma_f32_16x16x32_bf16 v[92:95], v[100:103], v[132:135], v[92:95]
	s_waitcnt vmcnt(1)
	v_mfma_f32_16x16x32_bf16 v[88:91], v[104:107], v[132:135], v[88:91]
	s_waitcnt vmcnt(0) lgkmcnt(0)
	v_mfma_f32_16x16x32_bf16 v[84:87], v[108:111], v[132:135], v[84:87]
	v_cvt_pk_bf16_f32 v132, v187, v189
	v_cvt_pk_bf16_f32 v133, v191, v193
	v_cvt_pk_bf16_f32 v134, v195, v197
	v_cvt_pk_bf16_f32 v135, v199, v201
	v_mfma_f32_16x16x32_bf16 v[186:189], v[116:119], v[48:51], 0
	s_nop 0
	v_mfma_f32_16x16x32_bf16 v[80:83], v[96:99], v[132:135], v[80:83]
	v_mfma_f32_16x16x32_bf16 v[76:79], v[100:103], v[132:135], v[76:79]
	v_mfma_f32_16x16x32_bf16 v[72:75], v[104:107], v[132:135], v[72:75]
	v_mfma_f32_16x16x32_bf16 v[68:71], v[108:111], v[132:135], v[68:71]
	v_mfma_f32_16x16x32_bf16 v[132:135], v[124:127], v[48:51], 0
	v_mfma_f32_16x16x32_bf16 v[124:127], v[124:127], v[56:59], 0
	v_mfma_f32_16x16x32_bf16 v[132:135], v[120:123], v[52:55], v[132:135]
	v_mfma_f32_16x16x32_bf16 v[120:123], v[120:123], v[60:63], v[124:127]
	v_mfma_f32_16x16x32_bf16 v[116:119], v[116:119], v[56:59], 0
	s_nop 5
	v_fma_f32 v128, v132, s33, -v183
	v_exp_f32_e32 v128, v128
	v_fma_f32 v133, v133, s33, -v183
	v_mfma_f32_16x16x32_bf16 v[186:189], v[112:115], v[52:55], v[186:189]
	v_exp_f32_e32 v133, v133
	v_fma_f32 v134, v134, s33, -v183
	v_exp_f32_e32 v134, v134
	v_mfma_f32_16x16x32_bf16 v[112:115], v[112:115], v[60:63], v[116:119]
	v_fma_f32 v135, v135, s33, -v183
	s_nop 2
	v_fma_f32 v132, v186, s33, -v183
	v_fma_f32 v186, v188, s33, -v183
	v_fma_f32 v116, v120, s33, -v184
	v_fma_f32 v117, v121, s33, -v184
	v_exp_f32_e32 v116, v116
	v_exp_f32_e32 v118, v117
	v_fma_f32 v117, v122, s33, -v184
	v_exp_f32_e32 v120, v117
	v_fma_f32 v117, v123, s33, -v184
	v_lshrrev_b32_e32 v188, v137, v204
	v_exp_f32_e32 v122, v117
	v_bfe_i32 v212, v188, 0, 1
	v_bfe_i32 v213, v185, 0, 1
	v_bfe_i32 v215, v185, 1, 1
	v_exp_f32_e32 v135, v135
	v_and_b32_e32 v117, v116, v212
	v_bfe_i32 v214, v188, 1, 1
	v_fma_f32 v112, v112, s33, -v184
	v_and_b32_e32 v116, v128, v213
	v_bfe_i32 v217, v185, 2, 1
	v_exp_f32_e32 v112, v112
	v_and_b32_e32 v119, v118, v214
	v_bfe_i32 v216, v188, 2, 1
	v_exp_f32_e32 v132, v132
	v_and_b32_e32 v118, v133, v215
	v_fma_f32 v113, v113, s33, -v184
	v_bfe_i32 v219, v185, 3, 1
	v_and_b32_e32 v121, v120, v216
	v_bfe_i32 v218, v188, 3, 1
	v_fma_f32 v159, v187, s33, -v183
	v_and_b32_e32 v120, v134, v217
	v_exp_f32_e32 v113, v113
	v_exp_f32_e32 v159, v159
	v_and_b32_e32 v123, v122, v218
	v_bfe_i32 v220, v188, 4, 1
	v_fma_f32 v114, v114, s33, -v184
	v_and_b32_e32 v122, v135, v219
	v_bfe_i32 v221, v185, 4, 1
	v_exp_f32_e32 v114, v114
	v_exp_f32_e32 v186, v186
	v_and_b32_e32 v125, v112, v220
	v_bfe_i32 v222, v188, 5, 1
	v_fma_f32 v115, v115, s33, -v184
	v_and_b32_e32 v124, v132, v221
	v_bfe_i32 v223, v185, 5, 1
	v_fma_f32 v187, v189, s33, -v183
	v_exp_f32_e32 v115, v115
	v_and_b32_e32 v127, v113, v222
	v_bfe_i32 v224, v188, 6, 1
	v_exp_f32_e32 v187, v187
	v_and_b32_e32 v126, v159, v223
	v_bfe_i32 v225, v185, 6, 1
	v_bfe_i32 v226, v188, 7, 1
	s_nop 0
	v_and_b32_e32 v133, v114, v224
	v_bfe_i32 v227, v185, 7, 1
	s_nop 0
	v_and_b32_e32 v132, v186, v225
	s_nop 1
	v_and_b32_e32 v135, v115, v226
	v_pk_add_f32 v[112:113], v[116:117], v[118:119]
	v_pk_add_f32 v[114:115], v[120:121], v[122:123]
	v_and_b32_e32 v134, v187, v227
	v_pk_add_f32 v[112:113], v[112:113], v[114:115]
	v_pk_add_f32 v[114:115], v[124:125], v[126:127]
	v_pk_add_f32 v[186:187], v[132:133], v[134:135]
	s_nop 0
	v_pk_add_f32 v[114:115], v[114:115], v[186:187]
	s_nop 0
	v_pk_add_f32 v[186:187], v[112:113], v[114:115]
	v_cvt_pk_bf16_f32 v112, v116, v118
	v_cvt_pk_bf16_f32 v113, v120, v122
	v_cvt_pk_bf16_f32 v114, v124, v126
	v_cvt_pk_bf16_f32 v115, v132, v134
	v_pk_add_f32 v[142:143], v[142:143], v[186:187]
	s_nop 0
	v_mfma_f32_16x16x32_bf16 v[40:43], v[96:99], v[112:115], v[40:43]
	v_mfma_f32_16x16x32_bf16 v[32:35], v[100:103], v[112:115], v[32:35]
	v_mfma_f32_16x16x32_bf16 v[28:31], v[104:107], v[112:115], v[28:31]
	v_mfma_f32_16x16x32_bf16 v[20:23], v[108:111], v[112:115], v[20:23]
	v_cvt_pk_bf16_f32 v112, v117, v119
	v_cvt_pk_bf16_f32 v113, v121, v123
	v_cvt_pk_bf16_f32 v114, v125, v127
	v_cvt_pk_bf16_f32 v115, v133, v135
	s_nop 1
	v_mfma_f32_16x16x32_bf16 v[12:15], v[96:99], v[112:115], v[12:15]
	v_mfma_f32_16x16x32_bf16 v[8:11], v[100:103], v[112:115], v[8:11]
	v_mfma_f32_16x16x32_bf16 v[4:7], v[104:107], v[112:115], v[4:7]
	v_mfma_f32_16x16x32_bf16 v[0:3], v[108:111], v[112:115], v[0:3]
	s_cbranch_scc1 .LBB0_4861
